# v40 + XCD leader proceeds without waiting for its local-release atomic at all barrier sites
# baseline (speedup 1.0000x reference)
.LBB0_153:
	s_or_b64 exec, exec, s[6:7]
	v_mov_b32_e32 v1, 0x2000
	v_mov_b32_e32 v2, 1
	s_waitcnt vmcnt(0)
	s_nop 0
	global_atomic_add v1, v2, s[4:5] offset:1024
	s_nop 0
